# PP phase: f32 cache-output stores (never re-read by the kernel) marked nt so they do not displace the working set in L2
# speedup vs baseline: 1.0244x; 1.0103x over previous
.LBB0_1574:
	s_or_b64 exec, exec, s[6:7]
	v_mfma_f32_32x32x16_bf16 v[16:31], v[32:35], v[68:71], 0
	v_add_u32_e32 v126, v102, v74
	v_add_u32_e32 v127, 0x800, v126
	v_add_u32_e32 v128, 0x1000, v126
	v_add_u32_e32 v150, 0x1800, v126
	v_add_u32_e32 v151, 0x2000, v126
	v_add_u32_e32 v152, 0x2800, v126
	v_add_u32_e32 v153, 0x3000, v126
	v_mfma_f32_32x32x16_bf16 v[0:15], v[36:39], v[68:71], 0
	s_nop 3
	ds_write_b128 v108, v[16:19]
	ds_write_b128 v108, v[20:23] offset:32
	ds_write_b128 v108, v[24:27] offset:64
	ds_write_b128 v108, v[28:31] offset:96
	s_nop 3
	ds_write_b128 v108, v[0:3] offset:128
	v_add_u32_e32 v154, 0x3800, v126
	s_movk_i32 s6, 0xffef
	v_cmp_eq_u32_e64 s[36:37], s13, v85
	v_mfma_f32_32x32x16_bf16 v[16:31], v[40:43], v[68:71], 0
	ds_write_b128 v108, v[4:7] offset:160
	ds_write_b128 v108, v[8:11] offset:192
	ds_write_b128 v108, v[12:15] offset:224
	s_nop 8
	ds_write_b128 v108, v[16:19] offset:256
	ds_write_b128 v108, v[20:23] offset:288
	ds_write_b128 v108, v[24:27] offset:320
	ds_write_b128 v108, v[28:31] offset:352
	v_add_u32_e32 v116, 32, v116
	v_subrev_u32_e32 v115, 32, v115
	v_mfma_f32_32x32x16_bf16 v[0:15], v[44:47], v[68:71], 0
	s_nop 11
	ds_write_b128 v108, v[0:3] offset:384
	ds_write_b128 v108, v[4:7] offset:416
	ds_write_b128 v108, v[8:11] offset:448
	ds_write_b128 v108, v[12:15] offset:480
	s_waitcnt lgkmcnt(0)
	ds_read2_b64 v[0:3], v126 offset1:66
	ds_read2_b64 v[4:7], v126 offset0:132 offset1:198
	ds_read2_b64 v[8:11], v127 offset0:8 offset1:74
	ds_read2_b64 v[12:15], v127 offset0:140 offset1:206
	ds_read2_b64 v[16:19], v128 offset0:16 offset1:82
	ds_read2_b64 v[20:23], v128 offset0:148 offset1:214
	ds_read2_b64 v[24:27], v150 offset0:24 offset1:90
	ds_read2_b64 v[28:31], v150 offset0:156 offset1:222
	s_waitcnt lgkmcnt(7)
	v_pk_fma_f32 v[0:1], v[90:91], v[92:93], v[0:1] op_sel:[0,1,0] op_sel_hi:[1,0,1]
	ds_read2_b64 v[68:71], v151 offset0:32 offset1:98
	ds_read2_b64 v[118:121], v151 offset0:164 offset1:230
	v_pk_fma_f32 v[0:1], v[96:97], v[92:93], v[0:1]
	ds_read2_b64 v[122:125], v152 offset0:40 offset1:106
	ds_read2_b64 v[130:133], v152 offset0:172 offset1:238
	v_pk_fma_f32 v[2:3], v[90:91], v[0:1], v[2:3] op_sel:[0,1,0] op_sel_hi:[1,0,1]
	ds_read2_b64 v[134:137], v153 offset0:48 offset1:114
	ds_read2_b64 v[138:141], v153 offset0:180 offset1:246
	v_pk_fma_f32 v[2:3], v[96:97], v[0:1], v[2:3]
	ds_read2_b64 v[142:145], v154 offset0:56 offset1:122
	ds_read2_b64 v[146:149], v154 offset0:188 offset1:254
	ds_write2_b64 v126, v[0:1], v[2:3] offset1:66
	s_waitcnt lgkmcnt(14)
	v_pk_fma_f32 v[0:1], v[90:91], v[2:3], v[4:5] op_sel:[0,1,0] op_sel_hi:[1,0,1]
	s_or_b64 s[42:43], s[36:37], s[42:43]
	v_pk_fma_f32 v[0:1], v[96:97], v[2:3], v[0:1]
	s_nop 0
	v_pk_fma_f32 v[2:3], v[90:91], v[0:1], v[6:7] op_sel:[0,1,0] op_sel_hi:[1,0,1]
	s_nop 0
	v_pk_fma_f32 v[2:3], v[96:97], v[0:1], v[2:3]
	ds_write2_b64 v126, v[0:1], v[2:3] offset0:132 offset1:198
	v_pk_fma_f32 v[0:1], v[90:91], v[2:3], v[8:9] op_sel:[0,1,0] op_sel_hi:[1,0,1]
	s_nop 0
	v_pk_fma_f32 v[0:1], v[96:97], v[2:3], v[0:1]
	s_nop 0
	v_pk_fma_f32 v[2:3], v[90:91], v[0:1], v[10:11] op_sel:[0,1,0] op_sel_hi:[1,0,1]
	s_nop 0
	v_pk_fma_f32 v[2:3], v[96:97], v[0:1], v[2:3]
	ds_write2_b64 v127, v[0:1], v[2:3] offset0:8 offset1:74
	s_waitcnt lgkmcnt(14)
	v_pk_fma_f32 v[0:1], v[90:91], v[2:3], v[12:13] op_sel:[0,1,0] op_sel_hi:[1,0,1]
	s_nop 0
	v_pk_fma_f32 v[0:1], v[96:97], v[2:3], v[0:1]
	s_nop 0
	v_pk_fma_f32 v[2:3], v[90:91], v[0:1], v[14:15] op_sel:[0,1,0] op_sel_hi:[1,0,1]
	s_nop 0
	v_pk_fma_f32 v[2:3], v[96:97], v[0:1], v[2:3]
	ds_write2_b64 v127, v[0:1], v[2:3] offset0:140 offset1:206
	v_pk_fma_f32 v[0:1], v[90:91], v[2:3], v[16:17] op_sel:[0,1,0] op_sel_hi:[1,0,1]
	s_nop 0
	v_pk_fma_f32 v[0:1], v[96:97], v[2:3], v[0:1]
	s_nop 0
	v_pk_fma_f32 v[2:3], v[90:91], v[0:1], v[18:19] op_sel:[0,1,0] op_sel_hi:[1,0,1]
	s_nop 0
	v_pk_fma_f32 v[2:3], v[96:97], v[0:1], v[2:3]
	ds_write2_b64 v128, v[0:1], v[2:3] offset0:16 offset1:82
	s_waitcnt lgkmcnt(14)
	v_pk_fma_f32 v[0:1], v[90:91], v[2:3], v[20:21] op_sel:[0,1,0] op_sel_hi:[1,0,1]
	s_nop 0
	v_pk_fma_f32 v[0:1], v[96:97], v[2:3], v[0:1]
	s_nop 0
	v_pk_fma_f32 v[2:3], v[90:91], v[0:1], v[22:23] op_sel:[0,1,0] op_sel_hi:[1,0,1]
	s_nop 0
	v_pk_fma_f32 v[2:3], v[96:97], v[0:1], v[2:3]
	ds_write2_b64 v128, v[0:1], v[2:3] offset0:148 offset1:214
	v_pk_fma_f32 v[0:1], v[90:91], v[2:3], v[24:25] op_sel:[0,1,0] op_sel_hi:[1,0,1]
	s_nop 0
	v_pk_fma_f32 v[0:1], v[96:97], v[2:3], v[0:1]
	s_nop 0
	v_pk_fma_f32 v[2:3], v[90:91], v[0:1], v[26:27] op_sel:[0,1,0] op_sel_hi:[1,0,1]
	s_nop 0
	v_pk_fma_f32 v[2:3], v[96:97], v[0:1], v[2:3]
	ds_write2_b64 v150, v[0:1], v[2:3] offset0:24 offset1:90
	s_waitcnt lgkmcnt(14)
	v_pk_fma_f32 v[0:1], v[90:91], v[2:3], v[28:29] op_sel:[0,1,0] op_sel_hi:[1,0,1]
	s_nop 0
	v_pk_fma_f32 v[0:1], v[96:97], v[2:3], v[0:1]
	s_nop 0
	v_pk_fma_f32 v[2:3], v[90:91], v[0:1], v[30:31] op_sel:[0,1,0] op_sel_hi:[1,0,1]
	s_nop 0
	v_pk_fma_f32 v[2:3], v[96:97], v[0:1], v[2:3]
	ds_write2_b64 v150, v[0:1], v[2:3] offset0:156 offset1:222
	v_pk_fma_f32 v[0:1], v[90:91], v[2:3], v[68:69] op_sel:[0,1,0] op_sel_hi:[1,0,1]
	s_nop 0
	v_pk_fma_f32 v[0:1], v[96:97], v[2:3], v[0:1]
	s_nop 0
	v_pk_fma_f32 v[2:3], v[90:91], v[0:1], v[70:71] op_sel:[0,1,0] op_sel_hi:[1,0,1]
	s_waitcnt vmcnt(0)
	v_mov_b64_e32 v[70:71], v[66:67]
	v_pk_fma_f32 v[2:3], v[96:97], v[0:1], v[2:3]
	ds_write2_b64 v151, v[0:1], v[2:3] offset0:32 offset1:98
	s_waitcnt lgkmcnt(14)
	v_pk_fma_f32 v[0:1], v[90:91], v[2:3], v[118:119] op_sel:[0,1,0] op_sel_hi:[1,0,1]
	v_mov_b64_e32 v[68:69], v[64:65]
	v_pk_fma_f32 v[0:1], v[96:97], v[2:3], v[0:1]
	s_nop 0
	v_pk_fma_f32 v[2:3], v[90:91], v[0:1], v[120:121] op_sel:[0,1,0] op_sel_hi:[1,0,1]
	s_nop 0
	v_pk_fma_f32 v[2:3], v[96:97], v[0:1], v[2:3]
	ds_write2_b64 v151, v[0:1], v[2:3] offset0:164 offset1:230
	v_pk_fma_f32 v[0:1], v[90:91], v[2:3], v[122:123] op_sel:[0,1,0] op_sel_hi:[1,0,1]
	s_nop 0
	v_pk_fma_f32 v[0:1], v[96:97], v[2:3], v[0:1]
	s_nop 0
	v_pk_fma_f32 v[2:3], v[90:91], v[0:1], v[124:125] op_sel:[0,1,0] op_sel_hi:[1,0,1]
	s_nop 0
	v_pk_fma_f32 v[2:3], v[96:97], v[0:1], v[2:3]
	ds_write2_b64 v152, v[0:1], v[2:3] offset0:40 offset1:106
	s_waitcnt lgkmcnt(14)
	v_pk_fma_f32 v[0:1], v[90:91], v[2:3], v[130:131] op_sel:[0,1,0] op_sel_hi:[1,0,1]
	s_nop 0
	v_pk_fma_f32 v[0:1], v[96:97], v[2:3], v[0:1]
	s_nop 0
	v_pk_fma_f32 v[2:3], v[90:91], v[0:1], v[132:133] op_sel:[0,1,0] op_sel_hi:[1,0,1]
	s_nop 0
	v_pk_fma_f32 v[2:3], v[96:97], v[0:1], v[2:3]
	ds_write2_b64 v152, v[0:1], v[2:3] offset0:172 offset1:238
	v_pk_fma_f32 v[0:1], v[90:91], v[2:3], v[134:135] op_sel:[0,1,0] op_sel_hi:[1,0,1]
	s_nop 0
	v_pk_fma_f32 v[0:1], v[96:97], v[2:3], v[0:1]
	s_nop 0
	v_pk_fma_f32 v[2:3], v[90:91], v[0:1], v[136:137] op_sel:[0,1,0] op_sel_hi:[1,0,1]
	s_nop 0
	v_pk_fma_f32 v[2:3], v[96:97], v[0:1], v[2:3]
	ds_write2_b64 v153, v[0:1], v[2:3] offset0:48 offset1:114
	s_waitcnt lgkmcnt(14)
	v_pk_fma_f32 v[0:1], v[90:91], v[2:3], v[138:139] op_sel:[0,1,0] op_sel_hi:[1,0,1]
	s_nop 0
	v_pk_fma_f32 v[0:1], v[96:97], v[2:3], v[0:1]
	s_nop 0
	v_pk_fma_f32 v[2:3], v[90:91], v[0:1], v[140:141] op_sel:[0,1,0] op_sel_hi:[1,0,1]
	s_nop 0
	v_pk_fma_f32 v[2:3], v[96:97], v[0:1], v[2:3]
	ds_write2_b64 v153, v[0:1], v[2:3] offset0:180 offset1:246
	v_pk_fma_f32 v[0:1], v[90:91], v[2:3], v[142:143] op_sel:[0,1,0] op_sel_hi:[1,0,1]
	s_nop 0
	v_pk_fma_f32 v[0:1], v[96:97], v[2:3], v[0:1]
	s_nop 0
	v_pk_fma_f32 v[2:3], v[90:91], v[0:1], v[144:145] op_sel:[0,1,0] op_sel_hi:[1,0,1]
	s_nop 0
	v_pk_fma_f32 v[2:3], v[96:97], v[0:1], v[2:3]
	ds_write2_b64 v154, v[0:1], v[2:3] offset0:56 offset1:122
	s_waitcnt lgkmcnt(14)
	v_pk_fma_f32 v[0:1], v[90:91], v[2:3], v[146:147] op_sel:[0,1,0] op_sel_hi:[1,0,1]
	s_nop 0
	v_pk_fma_f32 v[0:1], v[96:97], v[2:3], v[0:1]
	s_nop 0
	v_pk_fma_f32 v[2:3], v[90:91], v[0:1], v[148:149] op_sel:[0,1,0] op_sel_hi:[1,0,1]
	s_nop 0
	v_pk_fma_f32 v[92:93], v[96:97], v[0:1], v[2:3]
	ds_write2_b64 v154, v[0:1], v[92:93] offset0:188 offset1:254
	s_waitcnt lgkmcnt(0)
	ds_read_b128 v[0:3], v109
	ds_read_b128 v[4:7], v109 offset:16
	ds_read_b128 v[8:11], v109 offset:128
	ds_read_b128 v[12:15], v109 offset:256
	ds_read_b128 v[16:19], v109 offset:400
	s_waitcnt lgkmcnt(4)
	v_cvt_pk_bf16_f32 v0, v0, v1
	v_cvt_pk_bf16_f32 v1, v2, v3
	s_waitcnt lgkmcnt(3)
	v_cvt_pk_bf16_f32 v2, v4, v5
	v_cvt_pk_bf16_f32 v3, v6, v7
	ds_read_b128 v[4:7], v109 offset:144
	s_waitcnt lgkmcnt(3)
	v_cvt_pk_bf16_f32 v8, v8, v9
	v_mfma_f32_16x16x32_bf16 v[0:3], v[48:51], v[0:3], 0
	v_cvt_pk_bf16_f32 v9, v10, v11
	s_waitcnt lgkmcnt(0)
	v_cvt_pk_bf16_f32 v10, v4, v5
	v_cvt_pk_bf16_f32 v11, v6, v7
	ds_read_b128 v[4:7], v109 offset:272
	s_nop 0
	v_mfma_f32_16x16x32_bf16 v[0:3], v[52:55], v[8:11], v[0:3]
	v_cvt_pk_bf16_f32 v8, v12, v13
	v_cvt_pk_bf16_f32 v9, v14, v15
	ds_read_b128 v[12:15], v109 offset:384
	s_waitcnt lgkmcnt(1)
	v_cvt_pk_bf16_f32 v10, v4, v5
	v_cvt_pk_bf16_f32 v11, v6, v7
	v_cvt_pk_bf16_f32 v6, v16, v17
	v_cvt_pk_bf16_f32 v7, v18, v19
	v_mfma_f32_16x16x32_bf16 v[0:3], v[56:59], v[8:11], v[0:3]
	s_waitcnt lgkmcnt(0)
	v_cvt_pk_bf16_f32 v4, v12, v13
	v_cvt_pk_bf16_f32 v5, v14, v15
	ds_read_b128 v[16:19], v109 offset:8848
	s_nop 0
	v_mfma_f32_16x16x32_bf16 v[0:3], v[60:63], v[4:7], v[0:3]
	v_cndmask_b32_e64 v4, v87, v117, s[0:1]
	v_add_u32_e32 v8, v4, v114
	v_ashrrev_i32_e32 v9, 31, v8
	v_lshlrev_b64 v[8:9], 10, v[8:9]
	ds_read_b128 v[4:7], v109 offset:8448
	v_lshl_add_u64 v[12:13], v[94:95], 0, v[8:9]
	ds_read_b128 v[8:11], v109 offset:8464
	s_nop 0
	global_store_dwordx4 v[12:13], v[0:3], off nt
	ds_read_b128 v[12:15], v109 offset:8704
	v_subrev_u32_e32 v87, 32, v87
	s_waitcnt lgkmcnt(2)
	v_cvt_pk_bf16_f32 v0, v4, v5
	v_cvt_pk_bf16_f32 v1, v6, v7
	ds_read_b128 v[4:7], v109 offset:8576
	s_waitcnt lgkmcnt(2)
	v_cvt_pk_bf16_f32 v2, v8, v9
	v_cvt_pk_bf16_f32 v3, v10, v11
	ds_read_b128 v[8:11], v109 offset:8592
	s_waitcnt lgkmcnt(1)
	v_cvt_pk_bf16_f32 v4, v4, v5
	v_mfma_f32_16x16x32_bf16 v[0:3], v[48:51], v[0:3], 0
	v_cvt_pk_bf16_f32 v5, v6, v7
	s_waitcnt lgkmcnt(0)
	v_cvt_pk_bf16_f32 v6, v8, v9
	v_cvt_pk_bf16_f32 v7, v10, v11
	ds_read_b128 v[8:11], v109 offset:8720
	s_nop 0
	v_mfma_f32_16x16x32_bf16 v[0:3], v[52:55], v[4:7], v[0:3]
	v_cvt_pk_bf16_f32 v4, v12, v13
	v_cvt_pk_bf16_f32 v5, v14, v15
	ds_read_b128 v[12:15], v109 offset:8832
	s_waitcnt lgkmcnt(1)
	v_cvt_pk_bf16_f32 v6, v8, v9
	v_cvt_pk_bf16_f32 v7, v10, v11
	s_nop 1
	v_mfma_f32_16x16x32_bf16 v[0:3], v[56:59], v[4:7], v[0:3]
	s_waitcnt lgkmcnt(0)
	v_cvt_pk_bf16_f32 v4, v12, v13
	v_cvt_pk_bf16_f32 v5, v14, v15
	v_cvt_pk_bf16_f32 v6, v16, v17
	v_cvt_pk_bf16_f32 v7, v18, v19
	s_nop 1
	v_mfma_f32_16x16x32_bf16 v[0:3], v[60:63], v[4:7], v[0:3]
	v_add_u32_e32 v4, 16, v117
	v_xad_u32 v5, v117, s6, v113
	v_cndmask_b32_e64 v4, v5, v4, s[0:1]
	v_add_u32_e32 v4, v4, v114
	v_ashrrev_i32_e32 v5, 31, v4
	v_lshlrev_b64 v[4:5], 10, v[4:5]
	v_lshl_add_u64 v[4:5], v[94:95], 0, v[4:5]
	s_nop 0
	global_store_dwordx4 v[4:5], v[0:3], off nt
	s_waitcnt lgkmcnt(0)
	v_add_u32_e32 v117, 32, v117
	s_andn2_b64 exec, exec, s[42:43]
	s_cbranch_execz .LBB0_1577

.LBB0_1617:
	s_or_b64 exec, exec, s[6:7]
	v_lshl_or_b32 v98, v29, 1, s22
	v_ashrrev_i32_e32 v99, 31, v98
	v_lshlrev_b64 v[98:99], 8, v[98:99]
	v_lshl_add_u64 v[98:99], v[98:99], 0, v[128:129]
	s_waitcnt vmcnt(0)
	v_lshlrev_b32_e32 v248, 6, v226
	v_mov_b32_e32 v249, 0
	v_lshl_add_u64 v[246:247], v[76:77], 0, s[96:97]
	v_lshl_add_u64 v[246:247], v[246:247], 0, v[248:249]
	global_load_dword v245, v[246:247], off offset:-2048
	v_lshlrev_b32_e32 v116, 16, v20
	v_and_b32_e32 v117, 0xffff0000, v20
	v_lshlrev_b32_e32 v118, 16, v21
	v_and_b32_e32 v119, 0xffff0000, v21
	v_lshlrev_b32_e32 v20, 16, v22
	v_and_b32_e32 v21, 0xffff0000, v22
	v_lshlrev_b32_e32 v22, 16, v23
	v_and_b32_e32 v23, 0xffff0000, v23
	s_and_saveexec_b64 s[6:7], s[52:53]
	s_xor_b64 s[6:7], exec, s[6:7]
	s_cbranch_execz .LBB0_1623
	v_lshlrev_b32_e32 v124, 16, v114
	v_and_b32_e32 v125, 0xffff0000, v114
	v_lshlrev_b32_e32 v126, 16, v115
	v_and_b32_e32 v127, 0xffff0000, v115
	v_lshlrev_b64 v[114:115], 10, v[98:99]
	v_lshl_add_u64 v[130:131], v[60:61], 0, v[114:115]
	v_lshl_add_u64 v[114:115], v[62:63], 0, v[114:115]
	global_store_dwordx4 v[130:131], v[20:23], off nt
	global_store_dwordx4 v[114:115], v[124:127], off nt
	s_and_saveexec_b64 s[8:9], s[0:1]
	s_cbranch_execz .LBB0_1620
	v_lshlrev_b64 v[114:115], 9, v[98:99]
	v_lshl_add_u64 v[114:115], v[64:65], 0, v[114:115]
	global_store_dwordx4 v[114:115], v[24:27], off nt
.LBB0_1620:
	s_or_b64 exec, exec, s[8:9]
	s_and_saveexec_b64 s[8:9], s[36:37]
	s_cbranch_execz .LBB0_1622
	v_lshlrev_b64 v[24:25], 7, v[98:99]
	v_lshl_add_u64 v[24:25], v[66:67], 0, v[24:25]
	global_store_dwordx4 v[24:25], v[0:3], off nt

.LBB0_1631:
	s_or_b64 exec, exec, s[6:7]
	s_mov_b32 s6, 0x3e38aa3b
	v_pk_mul_f32 v[18:19], v[18:19], s[6:7] op_sel_hi:[1,0]
	v_pk_mul_f32 v[16:17], v[16:17], s[6:7] op_sel_hi:[1,0]
	s_mov_b32 s6, 0xb353000
	v_cvt_pk_bf16_f32 v16, v16, v17
	v_cvt_pk_bf16_f32 v17, v18, v19
	v_add_co_u32_e32 v18, vcc, s6, v24
	s_mov_b32 s6, 0x800000
	s_nop 0
	v_addc_co_u32_e32 v19, vcc, 0, v25, vcc
	global_store_dwordx2 v[18:19], v[16:17], off offset:1792
	v_pk_mul_f32 v[18:19], v[100:101], v[100:101]
	v_pk_mul_f32 v[16:17], v[102:103], v[102:103]
	v_add_f32_e32 v18, v18, v19
	v_add_f32_e32 v16, v16, v18
	v_add_f32_e32 v16, v17, v16
	s_waitcnt lgkmcnt(0)
	s_nop 1
	v_add_f32_dpp v16, v16, v16 quad_perm:[1,0,3,2] row_mask:0xf bank_mask:0xf
	s_waitcnt lgkmcnt(0)
	s_nop 1
	v_add_f32_dpp v16, v16, v16 quad_perm:[2,3,0,1] row_mask:0xf bank_mask:0xf
	s_waitcnt lgkmcnt(0)
	s_nop 1
	v_add_f32_dpp v16, v16, v16 row_half_mirror row_mask:0xf bank_mask:0xf
	s_waitcnt lgkmcnt(0)
	s_nop 1
	v_add_f32_dpp v16, v16, v16 row_mirror row_mask:0xf bank_mask:0xf
	v_fmamk_f32 v16, v16, 0x3c800000, v225
	v_cmp_gt_f32_e32 vcc, s6, v16
	v_mul_f32_e32 v17, 0x4b800000, v16
	s_nop 0
	v_cndmask_b32_e32 v16, v16, v17, vcc
	v_rsq_f32_e32 v16, v16
	s_nop 0
	v_mul_f32_e32 v17, 0x45800000, v16
	v_cndmask_b32_e32 v16, v16, v17, vcc
	v_pk_mul_f32 v[18:19], v[100:101], v[16:17] op_sel_hi:[1,0]
	v_pk_mul_f32 v[16:17], v[102:103], v[16:17] op_sel_hi:[1,0]
	v_pk_mul_f32 v[12:13], v[12:13], v[18:19]
	v_pk_mul_f32 v[14:15], v[14:15], v[16:17]
	s_mov_b64 vcc, 0
	s_and_saveexec_b64 s[6:7], s[52:53]
	s_xor_b64 s[6:7], exec, s[6:7]
	s_cbranch_execz .LBB0_1636
	s_and_saveexec_b64 s[8:9], s[0:1]
	s_cbranch_execz .LBB0_1634
	v_lshlrev_b64 v[16:17], 9, v[98:99]
	s_mov_b64 vcc, exec
	v_lshl_add_u64 v[16:17], v[68:69], 0, v[16:17]
	global_store_dwordx4 v[16:17], v[12:15], off nt

.LBB0_1642:
	s_or_b64 exec, exec, s[6:7]
	v_pk_mul_f32 v[10:11], v[82:83], v[82:83]
	v_pk_mul_f32 v[8:9], v[84:85], v[84:85]
	v_add_f32_e32 v10, v10, v11
	v_add_f32_e32 v8, v8, v10
	v_add_f32_e32 v8, v9, v8
	ds_bpermute_b32 v9, v12, v8
	s_waitcnt lgkmcnt(0)
	v_add_f32_e32 v8, v8, v9
	ds_bpermute_b32 v9, v13, v8
	s_waitcnt lgkmcnt(0)
	v_add_f32_e32 v8, v8, v9
	s_waitcnt lgkmcnt(0)
	s_nop 1
	v_add_f32_dpp v8, v8, v8 row_mirror row_mask:0xf bank_mask:0xf
	s_waitcnt lgkmcnt(0)
	s_nop 1
	v_add_f32_dpp v8, v8, v8 row_half_mirror row_mask:0xf bank_mask:0xf
	s_waitcnt lgkmcnt(0)
	s_nop 1
	v_add_f32_dpp v8, v8, v8 quad_perm:[2,3,0,1] row_mask:0xf bank_mask:0xf
	ds_bpermute_b32 v9, v21, v8
	s_and_saveexec_b64 s[6:7], s[0:1]
	s_cbranch_execz .LBB0_1646
	s_waitcnt lgkmcnt(0)
	v_add_f32_e32 v8, v8, v9
	v_fmamk_f32 v8, v8, 0x3c000000, v225
	s_mov_b32 s8, 0x800000
	v_mul_f32_e32 v9, 0x4b800000, v8
	v_cmp_gt_f32_e32 vcc, s8, v8
	s_nop 1
	v_cndmask_b32_e32 v8, v8, v9, vcc
	v_rsq_f32_e32 v8, v8
	s_nop 0
	v_mul_f32_e32 v9, 0x45800000, v8
	v_cndmask_b32_e32 v8, v8, v9, vcc
	v_pk_mul_f32 v[10:11], v[82:83], v[8:9] op_sel_hi:[1,0]
	v_pk_mul_f32 v[8:9], v[84:85], v[8:9] op_sel_hi:[1,0]
	v_pk_mul_f32 v[4:5], v[4:5], v[10:11]
	v_pk_mul_f32 v[6:7], v[6:7], v[8:9]
	s_and_saveexec_b64 s[8:9], s[52:53]
	s_cbranch_execz .LBB0_1645
	v_lshlrev_b64 v[8:9], 9, v[98:99]
	v_lshl_add_u64 v[8:9], v[70:71], 0, v[8:9]
	global_store_dwordx4 v[8:9], v[4:7], off nt
